# scan: chunk-start LDS reads in order of first use with counted waits; scan WGs 0-3 (T GEMM tail) skip the FFN2 weight copies
# speedup vs baseline: 1.0097x; 1.0046x over previous
; #define LAS __attribute__((address_space(3)))
; __device__ __forceinline__ float sum16(float x) { x = dpp_add<0xB1>(x); x = dpp_add<0x4E>(x); x = dpp_add<0x141>(x); x = dpp_add<0x140>(x); return x; }
; __device__ __forceinline__ void scan_step(f32x4& S, const ScanOps& o, LAS float* yp) {
;     f32x2 S0 = {S[0], S[1]}, S1 = {S[2], S[3]};
;     const f32x2 k0 = {o.kk[0], o.kk[1]}, k1 = {o.kk[2], o.kk[3]};
;     f32x2 t = S0 * k0; t = S1 * k1 + t;
;     const float sa = -sum16(t[0] + t[1]);
;     const f32x2 sav = {sa, sa}, vv = {o.v, o.v};
;     const f32x2 a0 = {o.ka[0], o.ka[1]}, a1 = {o.ka[2], o.ka[3]}, p0 = {o.kp[0], o.kp[1]}, p1 = {o.kp[2], o.kp[3]}, w0 = {o.w[0], o.w[1]}, w1 = {o.w[2], o.w[3]};
;     f32x2 u0 = a0 * sav; u0 = p0 * vv + u0; S0 = S0 * w0 + u0;
;     f32x2 u1 = a1 * sav; u1 = p1 * vv + u1; S1 = S1 * w1 + u1;
;     const f32x2 r0 = {o.rr[0], o.rr[1]}, r1 = {o.rr[2], o.rr[3]};
;     f32x2 y = S0 * r0; y = S1 * r1 + y;
;     *yp = y[0] + y[1];
;     S = (f32x4){S0[0], S0[1], S1[0], S1[1]};
; }
; __device__ __forceinline__ void scan_unit(const Ctx& p, int chain, int rq, LAS unsigned char* lds) {
;     ...
;         for (int ci = 0; ci < nch; ++ci) {
;             __syncthreads();
;             const LAS float* OP = B0 + (ci & 1) * SBUF_F + 4 * cl;
;             const LAS float* VP = B0 + (ci & 1) * SBUF_F + SCH * 320 + il * 16;
;             LAS float* Y = YB + (ci & 1) * YP_F + il * 16 + cl;
;             ScanOps oa, ob;
;             scan_load(oa, OP, VP, 0);
;             f32x2 vv = *(const LAS f32x2*)VP;
; #pragma unroll 1
;             for (int t = 0; t < SCH; t += 2) {
;                 scan_load(ob, OP, VP, t + 1);
;                 oa.v = vv[0]; ob.v = vv[1];
;                 scan_step(S, oa, Y + t * 256);
;                 scan_load(oa, OP, VP, (t + 2) & (SCH - 1));
;                 vv = *(const LAS f32x2*)(VP + ((t + 2) & (SCH - 1)));
;                 scan_step(S, ob, Y + (t + 1) * 256);
;             }
.LBB0_1714:
	s_and_b32 s12, s10, 1
	s_mulk_i32 s12, 0x5400
	s_lshl_b32 s13, s10, 14
	v_lshl_add_u32 v31, v26, 2, s12
	s_and_b32 s13, s13, 0x4000
	v_lshl_add_u32 v32, v28, 2, s12
	v_add_u32_e32 v33, s13, v29
	s_waitcnt lgkmcnt(0)
	s_barrier
	ds_read_b128 v[60:63], v31 offset:256
	ds_read_b128 v[64:67], v31 offset:768
	ds_read_b128 v[40:43], v32 offset:20480
	ds_read_b128 v[68:71], v31 offset:0
	ds_read_b128 v[72:75], v31 offset:512
	ds_read_b128 v[76:79], v31 offset:1024
	ds_read_b128 v[44:47], v32 offset:20496
	ds_read_b128 v[48:51], v32 offset:20512
	ds_read_b128 v[52:55], v32 offset:20528
	ds_read_b128 v[80:83], v31 offset:1536
	ds_read_b128 v[84:87], v31 offset:2048
	ds_read_b128 v[88:91], v31 offset:1280
	ds_read_b128 v[92:95], v31 offset:1792
	ds_read_b128 v[96:99], v31 offset:2304
	s_waitcnt lgkmcnt(13)
	v_mul_f32_e32 v100, v0, v60
	v_fmac_f32_e32 v100, v1, v61
	v_fmac_f32_e32 v100, v2, v62
	v_fmac_f32_e32 v100, v3, v63
	s_waitcnt lgkmcnt(11)
	v_mul_f32_e32 v104, v64, v40
	v_mul_f32_e32 v105, v65, v40
	v_add_f32_dpp v100, v100, v100 quad_perm:[1,0,3,2] row_mask:0xf bank_mask:0xf bound_ctrl:1
	v_mul_f32_e32 v106, v66, v40
	v_mul_f32_e32 v107, v67, v40
	v_add_f32_dpp v100, v100, v100 quad_perm:[2,3,0,1] row_mask:0xf bank_mask:0xf bound_ctrl:1
	s_waitcnt lgkmcnt(10)
	v_fmac_f32_e32 v104, v0, v68
	v_fmac_f32_e32 v105, v1, v69
	v_add_f32_dpp v100, v100, v100 row_half_mirror row_mask:0xf bank_mask:0xf bound_ctrl:1
	v_fmac_f32_e32 v106, v2, v70
	v_fmac_f32_e32 v107, v3, v71
	v_add_f32_dpp v100, v100, v100 row_mirror row_mask:0xf bank_mask:0xf bound_ctrl:1
	s_waitcnt lgkmcnt(9)
	v_fma_f32 v0, -v72, v100, v104
	v_fma_f32 v1, -v73, v100, v105
	v_fma_f32 v2, -v74, v100, v106
	v_fma_f32 v3, -v75, v100, v107
	s_waitcnt lgkmcnt(8)
	v_mul_f32_e32 v101, v0, v76
	v_fmac_f32_e32 v101, v1, v77
	v_fmac_f32_e32 v101, v2, v78
	v_fmac_f32_e32 v101, v3, v79
	ds_write_b32 v33, v101 offset:0
	ds_read_b128 v[60:63], v31 offset:2816
	ds_read_b128 v[64:67], v31 offset:3328
	ds_read_b128 v[68:71], v31 offset:2560
	ds_read_b128 v[72:75], v31 offset:3072
	ds_read_b128 v[76:79], v31 offset:3584
	s_waitcnt lgkmcnt(6)
	v_mul_f32_e32 v100, v0, v80
	v_fmac_f32_e32 v100, v1, v81
	v_fmac_f32_e32 v100, v2, v82
	v_fmac_f32_e32 v100, v3, v83
	v_mul_f32_e32 v104, v84, v41
	v_mul_f32_e32 v105, v85, v41
	v_add_f32_dpp v100, v100, v100 quad_perm:[1,0,3,2] row_mask:0xf bank_mask:0xf bound_ctrl:1
	v_mul_f32_e32 v106, v86, v41
	v_mul_f32_e32 v107, v87, v41
	v_add_f32_dpp v100, v100, v100 quad_perm:[2,3,0,1] row_mask:0xf bank_mask:0xf bound_ctrl:1
	v_fmac_f32_e32 v104, v0, v88
	v_fmac_f32_e32 v105, v1, v89
	v_add_f32_dpp v100, v100, v100 row_half_mirror row_mask:0xf bank_mask:0xf bound_ctrl:1
	v_fmac_f32_e32 v106, v2, v90
	v_fmac_f32_e32 v107, v3, v91
	v_add_f32_dpp v100, v100, v100 row_mirror row_mask:0xf bank_mask:0xf bound_ctrl:1
	v_fma_f32 v0, -v92, v100, v104
	v_fma_f32 v1, -v93, v100, v105
	v_fma_f32 v2, -v94, v100, v106
	v_fma_f32 v3, -v95, v100, v107
	v_mul_f32_e32 v101, v0, v96
	v_fmac_f32_e32 v101, v1, v97
	v_fmac_f32_e32 v101, v2, v98
	v_fmac_f32_e32 v101, v3, v99
	ds_write_b32 v33, v101 offset:1024
	ds_read_b128 v[80:83], v31 offset:4096
	ds_read_b128 v[84:87], v31 offset:4608
	ds_read_b128 v[88:91], v31 offset:3840
	ds_read_b128 v[92:95], v31 offset:4352
	ds_read_b128 v[96:99], v31 offset:4864
	s_waitcnt lgkmcnt(6)
	v_mul_f32_e32 v100, v0, v60
	v_fmac_f32_e32 v100, v1, v61
	v_fmac_f32_e32 v100, v2, v62
	v_fmac_f32_e32 v100, v3, v63
	v_mul_f32_e32 v104, v64, v42
	v_mul_f32_e32 v105, v65, v42
	v_add_f32_dpp v100, v100, v100 quad_perm:[1,0,3,2] row_mask:0xf bank_mask:0xf bound_ctrl:1
	v_mul_f32_e32 v106, v66, v42
	v_mul_f32_e32 v107, v67, v42
	v_add_f32_dpp v100, v100, v100 quad_perm:[2,3,0,1] row_mask:0xf bank_mask:0xf bound_ctrl:1
	v_fmac_f32_e32 v104, v0, v68
	v_fmac_f32_e32 v105, v1, v69
	v_add_f32_dpp v100, v100, v100 row_half_mirror row_mask:0xf bank_mask:0xf bound_ctrl:1
	v_fmac_f32_e32 v106, v2, v70
	v_fmac_f32_e32 v107, v3, v71
	v_add_f32_dpp v100, v100, v100 row_mirror row_mask:0xf bank_mask:0xf bound_ctrl:1
	v_fma_f32 v0, -v72, v100, v104
	v_fma_f32 v1, -v73, v100, v105
	v_fma_f32 v2, -v74, v100, v106
	v_fma_f32 v3, -v75, v100, v107
	v_mul_f32_e32 v101, v0, v76
	v_fmac_f32_e32 v101, v1, v77
	v_fmac_f32_e32 v101, v2, v78
	v_fmac_f32_e32 v101, v3, v79
	ds_write_b32 v33, v101 offset:2048
	ds_read_b128 v[60:63], v31 offset:5376
	ds_read_b128 v[64:67], v31 offset:5888
	ds_read_b128 v[68:71], v31 offset:5120
	ds_read_b128 v[72:75], v31 offset:5632
	ds_read_b128 v[76:79], v31 offset:6144
	s_waitcnt lgkmcnt(6)
	v_mul_f32_e32 v100, v0, v80
	v_fmac_f32_e32 v100, v1, v81
	v_fmac_f32_e32 v100, v2, v82
	v_fmac_f32_e32 v100, v3, v83
	v_mul_f32_e32 v104, v84, v43
	v_mul_f32_e32 v105, v85, v43
	v_add_f32_dpp v100, v100, v100 quad_perm:[1,0,3,2] row_mask:0xf bank_mask:0xf bound_ctrl:1
	v_mul_f32_e32 v106, v86, v43
	v_mul_f32_e32 v107, v87, v43
	v_add_f32_dpp v100, v100, v100 quad_perm:[2,3,0,1] row_mask:0xf bank_mask:0xf bound_ctrl:1
	v_fmac_f32_e32 v104, v0, v88
	v_fmac_f32_e32 v105, v1, v89
	v_add_f32_dpp v100, v100, v100 row_half_mirror row_mask:0xf bank_mask:0xf bound_ctrl:1
	v_fmac_f32_e32 v106, v2, v90
	v_fmac_f32_e32 v107, v3, v91
	v_add_f32_dpp v100, v100, v100 row_mirror row_mask:0xf bank_mask:0xf bound_ctrl:1
	v_fma_f32 v0, -v92, v100, v104
	v_fma_f32 v1, -v93, v100, v105
	v_fma_f32 v2, -v94, v100, v106
	v_fma_f32 v3, -v95, v100, v107
	v_mul_f32_e32 v101, v0, v96
	v_fmac_f32_e32 v101, v1, v97
	v_fmac_f32_e32 v101, v2, v98
	v_fmac_f32_e32 v101, v3, v99
	ds_write_b32 v33, v101 offset:3072
	ds_read_b128 v[80:83], v31 offset:6656
	ds_read_b128 v[84:87], v31 offset:7168
	ds_read_b128 v[88:91], v31 offset:6400
	ds_read_b128 v[92:95], v31 offset:6912
	ds_read_b128 v[96:99], v31 offset:7424
	s_waitcnt lgkmcnt(6)
; #define LAS __attribute__((address_space(3)))
; __device__ __forceinline__ float sum16(float x) { x = dpp_add<0xB1>(x); x = dpp_add<0x4E>(x); x = dpp_add<0x141>(x); x = dpp_add<0x140>(x); return x; }
; __device__ __forceinline__ void scan_step(f32x4& S, const ScanOps& o, LAS float* yp) {
;     f32x2 S0 = {S[0], S[1]}, S1 = {S[2], S[3]};
;     const f32x2 k0 = {o.kk[0], o.kk[1]}, k1 = {o.kk[2], o.kk[3]};
;     f32x2 t = S0 * k0; t = S1 * k1 + t;
;     const float sa = -sum16(t[0] + t[1]);
;     const f32x2 sav = {sa, sa}, vv = {o.v, o.v};
;     const f32x2 a0 = {o.ka[0], o.ka[1]}, a1 = {o.ka[2], o.ka[3]}, p0 = {o.kp[0], o.kp[1]}, p1 = {o.kp[2], o.kp[3]}, w0 = {o.w[0], o.w[1]}, w1 = {o.w[2], o.w[3]};
;     f32x2 u0 = a0 * sav; u0 = p0 * vv + u0; S0 = S0 * w0 + u0;
;     f32x2 u1 = a1 * sav; u1 = p1 * vv + u1; S1 = S1 * w1 + u1;
;     const f32x2 r0 = {o.rr[0], o.rr[1]}, r1 = {o.rr[2], o.rr[3]};
;     f32x2 y = S0 * r0; y = S1 * r1 + y;
;     *yp = y[0] + y[1];
;     S = (f32x4){S0[0], S0[1], S1[0], S1[1]};
; }
; __device__ __forceinline__ void scan_unit(const Ctx& p, int chain, int rq, LAS unsigned char* lds) {
;     ...
;             for (int t = 0; t < SCH; t += 2) {
;                 scan_load(ob, OP, VP, t + 1);
;                 oa.v = vv[0]; ob.v = vv[1];
;                 scan_step(S, oa, Y + t * 256);
;                 scan_load(oa, OP, VP, (t + 2) & (SCH - 1));
;                 vv = *(const LAS f32x2*)(VP + ((t + 2) & (SCH - 1)));
;                 scan_step(S, ob, Y + (t + 1) * 256);
;             }
	v_mul_f32_e32 v100, v0, v60
	v_fmac_f32_e32 v100, v1, v61
	v_fmac_f32_e32 v100, v2, v62
	v_fmac_f32_e32 v100, v3, v63
	v_mul_f32_e32 v104, v64, v44
	v_mul_f32_e32 v105, v65, v44
	v_add_f32_dpp v100, v100, v100 quad_perm:[1,0,3,2] row_mask:0xf bank_mask:0xf bound_ctrl:1
	v_mul_f32_e32 v106, v66, v44
	v_mul_f32_e32 v107, v67, v44
	v_add_f32_dpp v100, v100, v100 quad_perm:[2,3,0,1] row_mask:0xf bank_mask:0xf bound_ctrl:1
	v_fmac_f32_e32 v104, v0, v68
	v_fmac_f32_e32 v105, v1, v69
	v_add_f32_dpp v100, v100, v100 row_half_mirror row_mask:0xf bank_mask:0xf bound_ctrl:1
	v_fmac_f32_e32 v106, v2, v70
	v_fmac_f32_e32 v107, v3, v71
	v_add_f32_dpp v100, v100, v100 row_mirror row_mask:0xf bank_mask:0xf bound_ctrl:1
	v_fma_f32 v0, -v72, v100, v104
	v_fma_f32 v1, -v73, v100, v105
	v_fma_f32 v2, -v74, v100, v106
	v_fma_f32 v3, -v75, v100, v107
	v_mul_f32_e32 v101, v0, v76
	v_fmac_f32_e32 v101, v1, v77
	v_fmac_f32_e32 v101, v2, v78
	v_fmac_f32_e32 v101, v3, v79
	ds_write_b32 v33, v101 offset:4096
	ds_read_b128 v[60:63], v31 offset:7936
	ds_read_b128 v[64:67], v31 offset:8448
	ds_read_b128 v[68:71], v31 offset:7680
	ds_read_b128 v[72:75], v31 offset:8192
	ds_read_b128 v[76:79], v31 offset:8704
	s_waitcnt lgkmcnt(6)
	v_mul_f32_e32 v100, v0, v80
	v_fmac_f32_e32 v100, v1, v81
	v_fmac_f32_e32 v100, v2, v82
	v_fmac_f32_e32 v100, v3, v83
	v_mul_f32_e32 v104, v84, v45
	v_mul_f32_e32 v105, v85, v45
	v_add_f32_dpp v100, v100, v100 quad_perm:[1,0,3,2] row_mask:0xf bank_mask:0xf bound_ctrl:1
	v_mul_f32_e32 v106, v86, v45
	v_mul_f32_e32 v107, v87, v45
	v_add_f32_dpp v100, v100, v100 quad_perm:[2,3,0,1] row_mask:0xf bank_mask:0xf bound_ctrl:1
	v_fmac_f32_e32 v104, v0, v88
	v_fmac_f32_e32 v105, v1, v89
	v_add_f32_dpp v100, v100, v100 row_half_mirror row_mask:0xf bank_mask:0xf bound_ctrl:1
	v_fmac_f32_e32 v106, v2, v90
	v_fmac_f32_e32 v107, v3, v91
	v_add_f32_dpp v100, v100, v100 row_mirror row_mask:0xf bank_mask:0xf bound_ctrl:1
	v_fma_f32 v0, -v92, v100, v104
	v_fma_f32 v1, -v93, v100, v105
	v_fma_f32 v2, -v94, v100, v106
	v_fma_f32 v3, -v95, v100, v107
	v_mul_f32_e32 v101, v0, v96
	v_fmac_f32_e32 v101, v1, v97
	v_fmac_f32_e32 v101, v2, v98
	v_fmac_f32_e32 v101, v3, v99
	ds_write_b32 v33, v101 offset:5120
	ds_read_b128 v[80:83], v31 offset:9216
	ds_read_b128 v[84:87], v31 offset:9728
	ds_read_b128 v[88:91], v31 offset:8960
	ds_read_b128 v[92:95], v31 offset:9472
	ds_read_b128 v[96:99], v31 offset:9984
	s_waitcnt lgkmcnt(6)
	v_mul_f32_e32 v100, v0, v60
	v_fmac_f32_e32 v100, v1, v61
	v_fmac_f32_e32 v100, v2, v62
	v_fmac_f32_e32 v100, v3, v63
	v_mul_f32_e32 v104, v64, v46
	v_mul_f32_e32 v105, v65, v46
	v_add_f32_dpp v100, v100, v100 quad_perm:[1,0,3,2] row_mask:0xf bank_mask:0xf bound_ctrl:1
	v_mul_f32_e32 v106, v66, v46
	v_mul_f32_e32 v107, v67, v46
	v_add_f32_dpp v100, v100, v100 quad_perm:[2,3,0,1] row_mask:0xf bank_mask:0xf bound_ctrl:1
	v_fmac_f32_e32 v104, v0, v68
	v_fmac_f32_e32 v105, v1, v69
	v_add_f32_dpp v100, v100, v100 row_half_mirror row_mask:0xf bank_mask:0xf bound_ctrl:1
	v_fmac_f32_e32 v106, v2, v70
	v_fmac_f32_e32 v107, v3, v71
	v_add_f32_dpp v100, v100, v100 row_mirror row_mask:0xf bank_mask:0xf bound_ctrl:1
	v_fma_f32 v0, -v72, v100, v104
	v_fma_f32 v1, -v73, v100, v105
	v_fma_f32 v2, -v74, v100, v106
	v_fma_f32 v3, -v75, v100, v107
	v_mul_f32_e32 v101, v0, v76
	v_fmac_f32_e32 v101, v1, v77
	v_fmac_f32_e32 v101, v2, v78
	v_fmac_f32_e32 v101, v3, v79
	ds_write_b32 v33, v101 offset:6144
	ds_read_b128 v[60:63], v31 offset:10496
	ds_read_b128 v[64:67], v31 offset:11008
	ds_read_b128 v[68:71], v31 offset:10240
	ds_read_b128 v[72:75], v31 offset:10752
	ds_read_b128 v[76:79], v31 offset:11264
	s_waitcnt lgkmcnt(6)
	v_mul_f32_e32 v100, v0, v80
	v_fmac_f32_e32 v100, v1, v81
	v_fmac_f32_e32 v100, v2, v82
	v_fmac_f32_e32 v100, v3, v83
	v_mul_f32_e32 v104, v84, v47
	v_mul_f32_e32 v105, v85, v47
	v_add_f32_dpp v100, v100, v100 quad_perm:[1,0,3,2] row_mask:0xf bank_mask:0xf bound_ctrl:1
	v_mul_f32_e32 v106, v86, v47
	v_mul_f32_e32 v107, v87, v47
	v_add_f32_dpp v100, v100, v100 quad_perm:[2,3,0,1] row_mask:0xf bank_mask:0xf bound_ctrl:1
	v_fmac_f32_e32 v104, v0, v88
	v_fmac_f32_e32 v105, v1, v89
	v_add_f32_dpp v100, v100, v100 row_half_mirror row_mask:0xf bank_mask:0xf bound_ctrl:1
	v_fmac_f32_e32 v106, v2, v90
	v_fmac_f32_e32 v107, v3, v91
	v_add_f32_dpp v100, v100, v100 row_mirror row_mask:0xf bank_mask:0xf bound_ctrl:1
	v_fma_f32 v0, -v92, v100, v104
	v_fma_f32 v1, -v93, v100, v105
	v_fma_f32 v2, -v94, v100, v106
	v_fma_f32 v3, -v95, v100, v107
	v_mul_f32_e32 v101, v0, v96
	v_fmac_f32_e32 v101, v1, v97
	v_fmac_f32_e32 v101, v2, v98
	v_fmac_f32_e32 v101, v3, v99
	ds_write_b32 v33, v101 offset:7168
	ds_read_b128 v[80:83], v31 offset:11776
	ds_read_b128 v[84:87], v31 offset:12288
	ds_read_b128 v[88:91], v31 offset:11520
	ds_read_b128 v[92:95], v31 offset:12032
	ds_read_b128 v[96:99], v31 offset:12544
	s_waitcnt lgkmcnt(6)
	v_mul_f32_e32 v100, v0, v60
	v_fmac_f32_e32 v100, v1, v61
	v_fmac_f32_e32 v100, v2, v62
	v_fmac_f32_e32 v100, v3, v63
	v_mul_f32_e32 v104, v64, v48
	v_mul_f32_e32 v105, v65, v48
	v_add_f32_dpp v100, v100, v100 quad_perm:[1,0,3,2] row_mask:0xf bank_mask:0xf bound_ctrl:1
	v_mul_f32_e32 v106, v66, v48
	v_mul_f32_e32 v107, v67, v48
	v_add_f32_dpp v100, v100, v100 quad_perm:[2,3,0,1] row_mask:0xf bank_mask:0xf bound_ctrl:1
	v_fmac_f32_e32 v104, v0, v68
	v_fmac_f32_e32 v105, v1, v69
	v_add_f32_dpp v100, v100, v100 row_half_mirror row_mask:0xf bank_mask:0xf bound_ctrl:1
	v_fmac_f32_e32 v106, v2, v70
	v_fmac_f32_e32 v107, v3, v71
	v_add_f32_dpp v100, v100, v100 row_mirror row_mask:0xf bank_mask:0xf bound_ctrl:1
	v_fma_f32 v0, -v72, v100, v104
	v_fma_f32 v1, -v73, v100, v105
	v_fma_f32 v2, -v74, v100, v106
	v_fma_f32 v3, -v75, v100, v107
	v_mul_f32_e32 v101, v0, v76
	v_fmac_f32_e32 v101, v1, v77
	v_fmac_f32_e32 v101, v2, v78
	v_fmac_f32_e32 v101, v3, v79
	ds_write_b32 v33, v101 offset:8192
	ds_read_b128 v[60:63], v31 offset:13056
	ds_read_b128 v[64:67], v31 offset:13568
	ds_read_b128 v[68:71], v31 offset:12800
	ds_read_b128 v[72:75], v31 offset:13312
	ds_read_b128 v[76:79], v31 offset:13824
	s_waitcnt lgkmcnt(6)
; #define LAS __attribute__((address_space(3)))
; __device__ __forceinline__ float sum16(float x) { x = dpp_add<0xB1>(x); x = dpp_add<0x4E>(x); x = dpp_add<0x141>(x); x = dpp_add<0x140>(x); return x; }
; __device__ __forceinline__ void scan_step(f32x4& S, const ScanOps& o, LAS float* yp) {
;     f32x2 S0 = {S[0], S[1]}, S1 = {S[2], S[3]};
;     const f32x2 k0 = {o.kk[0], o.kk[1]}, k1 = {o.kk[2], o.kk[3]};
;     f32x2 t = S0 * k0; t = S1 * k1 + t;
;     const float sa = -sum16(t[0] + t[1]);
;     const f32x2 sav = {sa, sa}, vv = {o.v, o.v};
;     const f32x2 a0 = {o.ka[0], o.ka[1]}, a1 = {o.ka[2], o.ka[3]}, p0 = {o.kp[0], o.kp[1]}, p1 = {o.kp[2], o.kp[3]}, w0 = {o.w[0], o.w[1]}, w1 = {o.w[2], o.w[3]};
;     f32x2 u0 = a0 * sav; u0 = p0 * vv + u0; S0 = S0 * w0 + u0;
;     f32x2 u1 = a1 * sav; u1 = p1 * vv + u1; S1 = S1 * w1 + u1;
;     const f32x2 r0 = {o.rr[0], o.rr[1]}, r1 = {o.rr[2], o.rr[3]};
;     f32x2 y = S0 * r0; y = S1 * r1 + y;
;     *yp = y[0] + y[1];
;     S = (f32x4){S0[0], S0[1], S1[0], S1[1]};
; }
; __device__ __forceinline__ void scan_unit(const Ctx& p, int chain, int rq, LAS unsigned char* lds) {
;     ...
;             for (int t = 0; t < SCH; t += 2) {
;                 scan_load(ob, OP, VP, t + 1);
;                 oa.v = vv[0]; ob.v = vv[1];
;                 scan_step(S, oa, Y + t * 256);
;                 scan_load(oa, OP, VP, (t + 2) & (SCH - 1));
;                 vv = *(const LAS f32x2*)(VP + ((t + 2) & (SCH - 1)));
;                 scan_step(S, ob, Y + (t + 1) * 256);
;             }
	v_mul_f32_e32 v100, v0, v80
	v_fmac_f32_e32 v100, v1, v81
	v_fmac_f32_e32 v100, v2, v82
	v_fmac_f32_e32 v100, v3, v83
	v_mul_f32_e32 v104, v84, v49
	v_mul_f32_e32 v105, v85, v49
	v_add_f32_dpp v100, v100, v100 quad_perm:[1,0,3,2] row_mask:0xf bank_mask:0xf bound_ctrl:1
	v_mul_f32_e32 v106, v86, v49
	v_mul_f32_e32 v107, v87, v49
	v_add_f32_dpp v100, v100, v100 quad_perm:[2,3,0,1] row_mask:0xf bank_mask:0xf bound_ctrl:1
	v_fmac_f32_e32 v104, v0, v88
	v_fmac_f32_e32 v105, v1, v89
	v_add_f32_dpp v100, v100, v100 row_half_mirror row_mask:0xf bank_mask:0xf bound_ctrl:1
	v_fmac_f32_e32 v106, v2, v90
	v_fmac_f32_e32 v107, v3, v91
	v_add_f32_dpp v100, v100, v100 row_mirror row_mask:0xf bank_mask:0xf bound_ctrl:1
	v_fma_f32 v0, -v92, v100, v104
	v_fma_f32 v1, -v93, v100, v105
	v_fma_f32 v2, -v94, v100, v106
	v_fma_f32 v3, -v95, v100, v107
	v_mul_f32_e32 v101, v0, v96
	v_fmac_f32_e32 v101, v1, v97
	v_fmac_f32_e32 v101, v2, v98
	v_fmac_f32_e32 v101, v3, v99
	ds_write_b32 v33, v101 offset:9216
	ds_read_b128 v[80:83], v31 offset:14336
	ds_read_b128 v[84:87], v31 offset:14848
	ds_read_b128 v[88:91], v31 offset:14080
	ds_read_b128 v[92:95], v31 offset:14592
	ds_read_b128 v[96:99], v31 offset:15104
	s_waitcnt lgkmcnt(6)
	v_mul_f32_e32 v100, v0, v60
	v_fmac_f32_e32 v100, v1, v61
	v_fmac_f32_e32 v100, v2, v62
	v_fmac_f32_e32 v100, v3, v63
	v_mul_f32_e32 v104, v64, v50
	v_mul_f32_e32 v105, v65, v50
	v_add_f32_dpp v100, v100, v100 quad_perm:[1,0,3,2] row_mask:0xf bank_mask:0xf bound_ctrl:1
	v_mul_f32_e32 v106, v66, v50
	v_mul_f32_e32 v107, v67, v50
	v_add_f32_dpp v100, v100, v100 quad_perm:[2,3,0,1] row_mask:0xf bank_mask:0xf bound_ctrl:1
	v_fmac_f32_e32 v104, v0, v68
	v_fmac_f32_e32 v105, v1, v69
	v_add_f32_dpp v100, v100, v100 row_half_mirror row_mask:0xf bank_mask:0xf bound_ctrl:1
	v_fmac_f32_e32 v106, v2, v70
	v_fmac_f32_e32 v107, v3, v71
	v_add_f32_dpp v100, v100, v100 row_mirror row_mask:0xf bank_mask:0xf bound_ctrl:1
	v_fma_f32 v0, -v72, v100, v104
	v_fma_f32 v1, -v73, v100, v105
	v_fma_f32 v2, -v74, v100, v106
	v_fma_f32 v3, -v75, v100, v107
	v_mul_f32_e32 v101, v0, v76
	v_fmac_f32_e32 v101, v1, v77
	v_fmac_f32_e32 v101, v2, v78
	v_fmac_f32_e32 v101, v3, v79
	ds_write_b32 v33, v101 offset:10240
	ds_read_b128 v[60:63], v31 offset:15616
	ds_read_b128 v[64:67], v31 offset:16128
	ds_read_b128 v[68:71], v31 offset:15360
	ds_read_b128 v[72:75], v31 offset:15872
	ds_read_b128 v[76:79], v31 offset:16384
	s_waitcnt lgkmcnt(6)
	v_mul_f32_e32 v100, v0, v80
	v_fmac_f32_e32 v100, v1, v81
	v_fmac_f32_e32 v100, v2, v82
	v_fmac_f32_e32 v100, v3, v83
	v_mul_f32_e32 v104, v84, v51
	v_mul_f32_e32 v105, v85, v51
	v_add_f32_dpp v100, v100, v100 quad_perm:[1,0,3,2] row_mask:0xf bank_mask:0xf bound_ctrl:1
	v_mul_f32_e32 v106, v86, v51
	v_mul_f32_e32 v107, v87, v51
	v_add_f32_dpp v100, v100, v100 quad_perm:[2,3,0,1] row_mask:0xf bank_mask:0xf bound_ctrl:1
	v_fmac_f32_e32 v104, v0, v88
	v_fmac_f32_e32 v105, v1, v89
	v_add_f32_dpp v100, v100, v100 row_half_mirror row_mask:0xf bank_mask:0xf bound_ctrl:1
	v_fmac_f32_e32 v106, v2, v90
	v_fmac_f32_e32 v107, v3, v91
	v_add_f32_dpp v100, v100, v100 row_mirror row_mask:0xf bank_mask:0xf bound_ctrl:1
	v_fma_f32 v0, -v92, v100, v104
	v_fma_f32 v1, -v93, v100, v105
	v_fma_f32 v2, -v94, v100, v106
	v_fma_f32 v3, -v95, v100, v107
	v_mul_f32_e32 v101, v0, v96
	v_fmac_f32_e32 v101, v1, v97
	v_fmac_f32_e32 v101, v2, v98
	v_fmac_f32_e32 v101, v3, v99
	ds_write_b32 v33, v101 offset:11264
	ds_read_b128 v[80:83], v31 offset:16896
	ds_read_b128 v[84:87], v31 offset:17408
	ds_read_b128 v[88:91], v31 offset:16640
	ds_read_b128 v[92:95], v31 offset:17152
	ds_read_b128 v[96:99], v31 offset:17664
	s_waitcnt lgkmcnt(6)
	v_mul_f32_e32 v100, v0, v60
	v_fmac_f32_e32 v100, v1, v61
	v_fmac_f32_e32 v100, v2, v62
	v_fmac_f32_e32 v100, v3, v63
	v_mul_f32_e32 v104, v64, v52
	v_mul_f32_e32 v105, v65, v52
	v_add_f32_dpp v100, v100, v100 quad_perm:[1,0,3,2] row_mask:0xf bank_mask:0xf bound_ctrl:1
	v_mul_f32_e32 v106, v66, v52
	v_mul_f32_e32 v107, v67, v52
	v_add_f32_dpp v100, v100, v100 quad_perm:[2,3,0,1] row_mask:0xf bank_mask:0xf bound_ctrl:1
	v_fmac_f32_e32 v104, v0, v68
	v_fmac_f32_e32 v105, v1, v69
	v_add_f32_dpp v100, v100, v100 row_half_mirror row_mask:0xf bank_mask:0xf bound_ctrl:1
	v_fmac_f32_e32 v106, v2, v70
	v_fmac_f32_e32 v107, v3, v71
	v_add_f32_dpp v100, v100, v100 row_mirror row_mask:0xf bank_mask:0xf bound_ctrl:1
	v_fma_f32 v0, -v72, v100, v104
	v_fma_f32 v1, -v73, v100, v105
	v_fma_f32 v2, -v74, v100, v106
	v_fma_f32 v3, -v75, v100, v107
	v_mul_f32_e32 v101, v0, v76
	v_fmac_f32_e32 v101, v1, v77
	v_fmac_f32_e32 v101, v2, v78
	v_fmac_f32_e32 v101, v3, v79
	ds_write_b32 v33, v101 offset:12288
	ds_read_b128 v[60:63], v31 offset:18176
	ds_read_b128 v[64:67], v31 offset:18688
	ds_read_b128 v[68:71], v31 offset:17920
	ds_read_b128 v[72:75], v31 offset:18432
	ds_read_b128 v[76:79], v31 offset:18944
	s_waitcnt lgkmcnt(6)
; #define LAS __attribute__((address_space(3)))
; __device__ __forceinline__ float sum16(float x) { x = dpp_add<0xB1>(x); x = dpp_add<0x4E>(x); x = dpp_add<0x141>(x); x = dpp_add<0x140>(x); return x; }
; __device__ __forceinline__ void scan_step(f32x4& S, const ScanOps& o, LAS float* yp) {
;     f32x2 S0 = {S[0], S[1]}, S1 = {S[2], S[3]};
;     const f32x2 k0 = {o.kk[0], o.kk[1]}, k1 = {o.kk[2], o.kk[3]};
;     f32x2 t = S0 * k0; t = S1 * k1 + t;
;     const float sa = -sum16(t[0] + t[1]);
;     const f32x2 sav = {sa, sa}, vv = {o.v, o.v};
;     const f32x2 a0 = {o.ka[0], o.ka[1]}, a1 = {o.ka[2], o.ka[3]}, p0 = {o.kp[0], o.kp[1]}, p1 = {o.kp[2], o.kp[3]}, w0 = {o.w[0], o.w[1]}, w1 = {o.w[2], o.w[3]};
;     f32x2 u0 = a0 * sav; u0 = p0 * vv + u0; S0 = S0 * w0 + u0;
;     f32x2 u1 = a1 * sav; u1 = p1 * vv + u1; S1 = S1 * w1 + u1;
;     const f32x2 r0 = {o.rr[0], o.rr[1]}, r1 = {o.rr[2], o.rr[3]};
;     f32x2 y = S0 * r0; y = S1 * r1 + y;
;     *yp = y[0] + y[1];
;     S = (f32x4){S0[0], S0[1], S1[0], S1[1]};
; }
; __device__ __forceinline__ void scan_unit(const Ctx& p, int chain, int rq, LAS unsigned char* lds) {
;     ...
;         for (int ci = 0; ci < nch; ++ci) {
;             __syncthreads();
;             const LAS float* OP = B0 + (ci & 1) * SBUF_F + 4 * cl;
;             const LAS float* VP = B0 + (ci & 1) * SBUF_F + SCH * 320 + il * 16;
;             LAS float* Y = YB + (ci & 1) * YP_F + il * 16 + cl;
;             ScanOps oa, ob;
;             scan_load(oa, OP, VP, 0);
;             f32x2 vv = *(const LAS f32x2*)VP;
; #pragma unroll 1
;             for (int t = 0; t < SCH; t += 2) {
;                 scan_load(ob, OP, VP, t + 1);
;                 oa.v = vv[0]; ob.v = vv[1];
;                 scan_step(S, oa, Y + t * 256);
;                 scan_load(oa, OP, VP, (t + 2) & (SCH - 1));
;                 vv = *(const LAS f32x2*)(VP + ((t + 2) & (SCH - 1)));
;                 scan_step(S, ob, Y + (t + 1) * 256);
;             }
;         }
;         __syncthreads();
;         *(f32x4*)sg = S;
	v_mul_f32_e32 v100, v0, v80
	v_fmac_f32_e32 v100, v1, v81
	v_fmac_f32_e32 v100, v2, v82
	v_fmac_f32_e32 v100, v3, v83
	v_mul_f32_e32 v104, v84, v53
	v_mul_f32_e32 v105, v85, v53
	v_add_f32_dpp v100, v100, v100 quad_perm:[1,0,3,2] row_mask:0xf bank_mask:0xf bound_ctrl:1
	v_mul_f32_e32 v106, v86, v53
	v_mul_f32_e32 v107, v87, v53
	v_add_f32_dpp v100, v100, v100 quad_perm:[2,3,0,1] row_mask:0xf bank_mask:0xf bound_ctrl:1
	v_fmac_f32_e32 v104, v0, v88
	v_fmac_f32_e32 v105, v1, v89
	v_add_f32_dpp v100, v100, v100 row_half_mirror row_mask:0xf bank_mask:0xf bound_ctrl:1
	v_fmac_f32_e32 v106, v2, v90
	v_fmac_f32_e32 v107, v3, v91
	v_add_f32_dpp v100, v100, v100 row_mirror row_mask:0xf bank_mask:0xf bound_ctrl:1
	v_fma_f32 v0, -v92, v100, v104
	v_fma_f32 v1, -v93, v100, v105
	v_fma_f32 v2, -v94, v100, v106
	v_fma_f32 v3, -v95, v100, v107
	v_mul_f32_e32 v101, v0, v96
	v_fmac_f32_e32 v101, v1, v97
	v_fmac_f32_e32 v101, v2, v98
	v_fmac_f32_e32 v101, v3, v99
	ds_write_b32 v33, v101 offset:13312
	ds_read_b128 v[80:83], v31 offset:19456
	ds_read_b128 v[84:87], v31 offset:19968
	ds_read_b128 v[88:91], v31 offset:19200
	ds_read_b128 v[92:95], v31 offset:19712
	ds_read_b128 v[96:99], v31 offset:20224
	s_waitcnt lgkmcnt(6)
	v_mul_f32_e32 v100, v0, v60
	v_fmac_f32_e32 v100, v1, v61
	v_fmac_f32_e32 v100, v2, v62
	v_fmac_f32_e32 v100, v3, v63
	v_mul_f32_e32 v104, v64, v54
	v_mul_f32_e32 v105, v65, v54
	v_add_f32_dpp v100, v100, v100 quad_perm:[1,0,3,2] row_mask:0xf bank_mask:0xf bound_ctrl:1
	v_mul_f32_e32 v106, v66, v54
	v_mul_f32_e32 v107, v67, v54
	v_add_f32_dpp v100, v100, v100 quad_perm:[2,3,0,1] row_mask:0xf bank_mask:0xf bound_ctrl:1
	v_fmac_f32_e32 v104, v0, v68
	v_fmac_f32_e32 v105, v1, v69
	v_add_f32_dpp v100, v100, v100 row_half_mirror row_mask:0xf bank_mask:0xf bound_ctrl:1
	v_fmac_f32_e32 v106, v2, v70
	v_fmac_f32_e32 v107, v3, v71
	v_add_f32_dpp v100, v100, v100 row_mirror row_mask:0xf bank_mask:0xf bound_ctrl:1
	v_fma_f32 v0, -v72, v100, v104
	v_fma_f32 v1, -v73, v100, v105
	v_fma_f32 v2, -v74, v100, v106
	v_fma_f32 v3, -v75, v100, v107
	v_mul_f32_e32 v101, v0, v76
	v_fmac_f32_e32 v101, v1, v77
	v_fmac_f32_e32 v101, v2, v78
	v_fmac_f32_e32 v101, v3, v79
	ds_write_b32 v33, v101 offset:14336
	s_waitcnt lgkmcnt(1)
	v_mul_f32_e32 v100, v0, v80
	v_fmac_f32_e32 v100, v1, v81
	v_fmac_f32_e32 v100, v2, v82
	v_fmac_f32_e32 v100, v3, v83
	v_mul_f32_e32 v104, v84, v55
	v_mul_f32_e32 v105, v85, v55
	v_add_f32_dpp v100, v100, v100 quad_perm:[1,0,3,2] row_mask:0xf bank_mask:0xf bound_ctrl:1
	v_mul_f32_e32 v106, v86, v55
	v_mul_f32_e32 v107, v87, v55
	v_add_f32_dpp v100, v100, v100 quad_perm:[2,3,0,1] row_mask:0xf bank_mask:0xf bound_ctrl:1
	v_fmac_f32_e32 v104, v0, v88
	v_fmac_f32_e32 v105, v1, v89
	v_add_f32_dpp v100, v100, v100 row_half_mirror row_mask:0xf bank_mask:0xf bound_ctrl:1
	v_fmac_f32_e32 v106, v2, v90
	v_fmac_f32_e32 v107, v3, v91
	v_add_f32_dpp v100, v100, v100 row_mirror row_mask:0xf bank_mask:0xf bound_ctrl:1
	v_fma_f32 v0, -v92, v100, v104
	v_fma_f32 v1, -v93, v100, v105
	v_fma_f32 v2, -v94, v100, v106
	v_fma_f32 v3, -v95, v100, v107
	v_mul_f32_e32 v101, v0, v96
	v_fmac_f32_e32 v101, v1, v97
	v_fmac_f32_e32 v101, v2, v98
	v_fmac_f32_e32 v101, v3, v99
	ds_write_b32 v33, v101 offset:15360
	s_add_i32 s10, s10, 1
	s_cmpk_eq_i32 s10, 0x100
	s_cbranch_scc0 .LBB0_1714
	s_setprio 0
	s_lshl_b32 s8, s28, 12
	v_lshl_or_b32 v4, v27, 8, s8
	v_mov_b32_e32 v5, 0
	v_lshl_add_u64 v[6:7], s[2:3], 0, v[4:5]
	v_lshlrev_b32_e32 v4, 2, v26
	v_lshl_add_u64 v[4:5], v[6:7], 0, v[4:5]
	v_add_co_u32_e32 v4, vcc, 0x8080000, v4
	s_mov_b64 s[2:3], 0
	s_nop 0
	v_addc_co_u32_e32 v5, vcc, 0, v5, vcc
	s_waitcnt lgkmcnt(0)
	s_barrier
	global_store_dwordx4 v[4:5], v[0:3], off

; #define LAS __attribute__((address_space(3)))
; __device__ __forceinline__ unsigned pk2(float lo, float hi) { f32x2 v = {lo, hi}; bf16x2_t b = __builtin_convertvector(v, bf16x2_t); return __builtin_bit_cast(unsigned, b); }
;     __device__ __forceinline__ const float* in(int i) const { return (const float*)ptr(i); }
;     __device__ __forceinline__ unsigned char* ws() const { return (unsigned char*)ptr(37); }
; #define ws (p.ws())
; __device__ __forceinline__ void transpose_item(const float* W, int K, int N, bf16_t* WT, int k0, int n0, int drow0, LAS float* scr, int lane) {
; #pragma unroll 8
;     for (int i = 0; i < 32; ++i) { const int kk = 2 * i + (lane >> 5); scr[kk * 33 + (lane & 31)] = W[(size_t)(k0 + kk) * N + n0 + (lane & 31)]; }
;     asm volatile("s_waitcnt lgkmcnt(0)" ::: "memory");
;     const int c = lane & 7;
; #pragma unroll
;     for (int j = 0; j < 4; ++j) { const int n = (lane >> 3) + 8 * j; const LAS float* s = scr + (8 * c) * 33 + n;
;         u32x4 o; o.x = pk2(s[0 * 33], s[1 * 33]); o.y = pk2(s[2 * 33], s[3 * 33]); o.z = pk2(s[4 * 33], s[5 * 33]); o.w = pk2(s[6 * 33], s[7 * 33]);
;         *(u32x4*)(WT + (size_t)(drow0 + n) * K + k0 + 8 * c) = o; }
;     asm volatile("s_waitcnt lgkmcnt(0)" ::: "memory");
; }
; __device__ __forceinline__ void ffn2_weights(const Ctx& p, LAS unsigned char* lds) {
;     const int tid = threadIdx.x, lane = tid & 63, wave = __builtin_amdgcn_readfirstlane(tid >> 6);
;     unsigned char* ws = p.ws();
;     LAS float* scr = (LAS float*)(lds + wave * 16384);
;     constexpr int I7 = 16 * 176, I8 = 44 * 32;
;     __syncthreads();
;     for (int it = ((int)blockIdx.x - 128) * 8 + wave; it < I7 + I8; it += 128 * 8) {
;         int r = it;
;         if (r < I7) { const int kb = r / 176, nb = r % 176; transpose_item(p.in(33), DM, NFF, (bf16_t*)(ws + WS_W3T), 64 * kb, 32 * nb, map_w1(32 * nb), scr, lane); continue; } r -= I7;
.Lscan_ffn2w:
	s_cmpk_lt_u32 s28, 4
	s_cbranch_scc1 .Lffn2w_done
	s_waitcnt vmcnt(0) lgkmcnt(0)
	s_barrier
	v_mov_b32_e32 v0, 0x23508
	v_mov_b32_e32 v1, 0x23510
	v_mov_b32_e32 v2, 0x23528
	ds_read_b64 v[4:5], v0
	ds_read_b64 v[6:7], v1
	ds_read_b64 v[8:9], v2
	v_readfirstlane_b32 s2, v180
	s_waitcnt lgkmcnt(0)
	v_readfirstlane_b32 s8, v4
	v_readfirstlane_b32 s9, v5
	v_readfirstlane_b32 s10, v6
	v_readfirstlane_b32 s11, v7
	v_readfirstlane_b32 s12, v8
	v_readfirstlane_b32 s13, v9
	s_nop 4
	s_lshr_b32 s27, s2, 6
	s_sub_u32 s26, s28, 4
	s_lshl_b32 s26, s26, 3
	s_add_i32 s26, s26, s27
	s_lshl_b32 s3, s27, 14
	v_and_b32_e32 v0, 63, v180
	v_lshrrev_b32_e32 v1, 3, v0
	v_and_b32_e32 v2, 7, v0
	v_mul_u32_u24_e32 v14, 0x84, v1
	v_lshl_add_u32 v14, v2, 4, v14
	v_add_u32_e32 v14, s3, v14
	v_mul_u32_u24_e32 v15, 0x420, v2
	v_lshl_add_u32 v15, v1, 2, v15
	v_add_u32_e32 v15, s3, v15
	v_mul_u32_u24_e32 v13, 0x5800, v1
	v_lshl_add_u32 v13, v2, 4, v13
	v_lshlrev_b32_e32 v4, 11, v1
	v_lshl_add_u32 v4, v2, 4, v4
	v_add_u32_e32 v5, 0x4000, v4
	v_add_u32_e32 v6, 0x8000, v4
	v_add_u32_e32 v7, 0xc000, v4
	s_add_u32 s18, s12, 0x1f00000
	s_addc_u32 s19, s13, 0
.Lffn2w_w3:
	s_cmpk_gt_u32 s26, 0xaff
	s_cbranch_scc1 .Lffn2w_w3_done
	s_mul_hi_u32 s4, s26, 0x1745d18
	s_mul_i32 s5, s4, 0xb0
	s_sub_u32 s5, s26, s5
	s_mul_i32 s6, s4, 0x160000
	s_lshl_b32 s7, s5, 7
	s_add_u32 s6, s6, s7
	s_add_u32 s14, s8, s6
	s_addc_u32 s15, s9, 0
	s_cmpk_lt_u32 s5, 0x58
	s_cselect_b32 s20, 0, 0x80
	s_cselect_b32 s21, 0, 0x58
	s_sub_u32 s5, s5, s21
	s_lshr_b32 s21, s5, 2
	s_lshl_b32 s21, s21, 8
	s_and_b32 s5, s5, 3
	s_lshl_b32 s5, s5, 5
	s_add_u32 s21, s21, s5
	s_add_u32 s21, s21, s20
	s_lshl_b32 s21, s21, 11
	s_lshl_b32 s4, s4, 7
	s_add_u32 s21, s21, s4
	s_add_u32 s16, s18, s21
	s_addc_u32 s17, s19, 0
	global_load_dwordx4 v[16:19], v13, s[14:15]
	v_add_u32_e32 v12, 0x2c000, v13
	global_load_dwordx4 v[20:23], v12, s[14:15]
	v_add_u32_e32 v12, 0x2c000, v12
	global_load_dwordx4 v[24:27], v12, s[14:15]
	v_add_u32_e32 v12, 0x2c000, v12
	global_load_dwordx4 v[28:31], v12, s[14:15]
	v_add_u32_e32 v12, 0x2c000, v12
	global_load_dwordx4 v[32:35], v12, s[14:15]
	v_add_u32_e32 v12, 0x2c000, v12
	global_load_dwordx4 v[36:39], v12, s[14:15]
	v_add_u32_e32 v12, 0x2c000, v12
	global_load_dwordx4 v[40:43], v12, s[14:15]
	v_add_u32_e32 v12, 0x2c000, v12
	global_load_dwordx4 v[44:47], v12, s[14:15]
	s_waitcnt vmcnt(7)
	ds_write_b32 v14, v16 offset:0
	ds_write_b32 v14, v17 offset:4
	ds_write_b32 v14, v18 offset:8
	ds_write_b32 v14, v19 offset:12
	s_waitcnt vmcnt(6)
	ds_write_b32 v14, v20 offset:1056
	ds_write_b32 v14, v21 offset:1060
	ds_write_b32 v14, v22 offset:1064
	ds_write_b32 v14, v23 offset:1068
	s_waitcnt vmcnt(5)
	ds_write_b32 v14, v24 offset:2112
	ds_write_b32 v14, v25 offset:2116
	ds_write_b32 v14, v26 offset:2120
	ds_write_b32 v14, v27 offset:2124
	s_waitcnt vmcnt(4)
	ds_write_b32 v14, v28 offset:3168
	ds_write_b32 v14, v29 offset:3172
	ds_write_b32 v14, v30 offset:3176
	ds_write_b32 v14, v31 offset:3180
	s_waitcnt vmcnt(3)
	ds_write_b32 v14, v32 offset:4224
	ds_write_b32 v14, v33 offset:4228
	ds_write_b32 v14, v34 offset:4232
	ds_write_b32 v14, v35 offset:4236
	s_waitcnt vmcnt(2)
	ds_write_b32 v14, v36 offset:5280
	ds_write_b32 v14, v37 offset:5284
	ds_write_b32 v14, v38 offset:5288
	ds_write_b32 v14, v39 offset:5292
	s_waitcnt vmcnt(1)
	ds_write_b32 v14, v40 offset:6336
	ds_write_b32 v14, v41 offset:6340
	ds_write_b32 v14, v42 offset:6344
	ds_write_b32 v14, v43 offset:6348
	s_waitcnt vmcnt(0)
	ds_write_b32 v14, v44 offset:7392
	ds_write_b32 v14, v45 offset:7396
	ds_write_b32 v14, v46 offset:7400
	ds_write_b32 v14, v47 offset:7404
	s_waitcnt lgkmcnt(0)
	ds_read2_b32 v[80:81], v15 offset0:0 offset1:33
	ds_read2_b32 v[82:83], v15 offset0:66 offset1:99
	ds_read2_b32 v[84:85], v15 offset0:132 offset1:165
	ds_read2_b32 v[86:87], v15 offset0:198 offset1:231
	ds_read2_b32 v[88:89], v15 offset0:8 offset1:41
	ds_read2_b32 v[90:91], v15 offset0:74 offset1:107
	ds_read2_b32 v[92:93], v15 offset0:140 offset1:173
	ds_read2_b32 v[94:95], v15 offset0:206 offset1:239
	s_waitcnt lgkmcnt(4)
	v_cvt_pk_bf16_f32 v112, v80, v81
	v_cvt_pk_bf16_f32 v113, v82, v83
	v_cvt_pk_bf16_f32 v114, v84, v85
	v_cvt_pk_bf16_f32 v115, v86, v87
	global_store_dwordx4 v4, v[112:115], s[16:17]
	s_waitcnt lgkmcnt(0)
	v_cvt_pk_bf16_f32 v116, v88, v89
	v_cvt_pk_bf16_f32 v117, v90, v91
	v_cvt_pk_bf16_f32 v118, v92, v93
	v_cvt_pk_bf16_f32 v119, v94, v95
	global_store_dwordx4 v5, v[116:119], s[16:17]
	ds_read2_b32 v[96:97], v15 offset0:16 offset1:49
	ds_read2_b32 v[98:99], v15 offset0:82 offset1:115
	ds_read2_b32 v[100:101], v15 offset0:148 offset1:181
	ds_read2_b32 v[102:103], v15 offset0:214 offset1:247
	ds_read2_b32 v[104:105], v15 offset0:24 offset1:57
	ds_read2_b32 v[106:107], v15 offset0:90 offset1:123
	ds_read2_b32 v[108:109], v15 offset0:156 offset1:189
	ds_read2_b32 v[110:111], v15 offset0:222 offset1:255
	s_waitcnt lgkmcnt(4)
	v_cvt_pk_bf16_f32 v120, v96, v97
	v_cvt_pk_bf16_f32 v121, v98, v99
	v_cvt_pk_bf16_f32 v122, v100, v101
	v_cvt_pk_bf16_f32 v123, v102, v103
	global_store_dwordx4 v6, v[120:123], s[16:17]
	s_waitcnt lgkmcnt(0)
	v_cvt_pk_bf16_f32 v124, v104, v105
	v_cvt_pk_bf16_f32 v125, v106, v107
	v_cvt_pk_bf16_f32 v126, v108, v109
	v_cvt_pk_bf16_f32 v127, v110, v111
	global_store_dwordx4 v7, v[124:127], s[16:17]
	s_addk_i32 s26, 0x3e0
	s_branch .Lffn2w_w3

; #define LAS __attribute__((address_space(3)))
; __device__ __forceinline__ unsigned pk2(float lo, float hi) { f32x2 v = {lo, hi}; bf16x2_t b = __builtin_convertvector(v, bf16x2_t); return __builtin_bit_cast(unsigned, b); }
;     __device__ __forceinline__ const float* in(int i) const { return (const float*)ptr(i); }
;     __device__ __forceinline__ unsigned char* ws() const { return (unsigned char*)ptr(37); }
; #define ws (p.ws())
; __device__ __forceinline__ void transpose_item(const float* W, int K, int N, bf16_t* WT, int k0, int n0, int drow0, LAS float* scr, int lane) {
; #pragma unroll 8
;     for (int i = 0; i < 32; ++i) { const int kk = 2 * i + (lane >> 5); scr[kk * 33 + (lane & 31)] = W[(size_t)(k0 + kk) * N + n0 + (lane & 31)]; }
;     asm volatile("s_waitcnt lgkmcnt(0)" ::: "memory");
;     const int c = lane & 7;
; #pragma unroll
;     for (int j = 0; j < 4; ++j) { const int n = (lane >> 3) + 8 * j; const LAS float* s = scr + (8 * c) * 33 + n;
;         u32x4 o; o.x = pk2(s[0 * 33], s[1 * 33]); o.y = pk2(s[2 * 33], s[3 * 33]); o.z = pk2(s[4 * 33], s[5 * 33]); o.w = pk2(s[6 * 33], s[7 * 33]);
;         *(u32x4*)(WT + (size_t)(drow0 + n) * K + k0 + 8 * c) = o; }
;     asm volatile("s_waitcnt lgkmcnt(0)" ::: "memory");
; }
; __device__ __forceinline__ void ffn2_weights(const Ctx& p, LAS unsigned char* lds) {
;     ...
;     for (int it = ((int)blockIdx.x - 128) * 8 + wave; it < I7 + I8; it += 128 * 8) {
;         int r = it;
;         if (r < I7) { const int kb = r / 176, nb = r % 176; transpose_item(p.in(33), DM, NFF, (bf16_t*)(ws + WS_W3T), 64 * kb, 32 * nb, map_w1(32 * nb), scr, lane); continue; } r -= I7;
;         { const int kb = r / 32, nb = r % 32; transpose_item(p.in(34), DFF, DM, (bf16_t*)(ws + WS_W4T), 64 * kb, 32 * nb, 32 * nb, scr, lane); }
;     }
.Lffn2w_w4:
	s_cmpk_gt_u32 s26, 0x57f
	s_cbranch_scc1 .Lffn2w_done
	s_lshr_b32 s4, s26, 5
	s_and_b32 s5, s26, 31
	s_lshl_b32 s6, s4, 18
	s_lshl_b32 s7, s5, 7
	s_add_u32 s6, s6, s7
	s_add_u32 s14, s10, s6
	s_addc_u32 s15, s11, 0
	s_mul_i32 s21, s5, 0x2c000
	s_lshl_b32 s4, s4, 7
	s_add_u32 s21, s21, s4
	s_add_u32 s16, s18, s21
	s_addc_u32 s17, s19, 0
	global_load_dwordx4 v[16:19], v13, s[14:15]
	v_add_u32_e32 v12, 0x8000, v13
	global_load_dwordx4 v[20:23], v12, s[14:15]
	v_add_u32_e32 v12, 0x8000, v12
	global_load_dwordx4 v[24:27], v12, s[14:15]
	v_add_u32_e32 v12, 0x8000, v12
	global_load_dwordx4 v[28:31], v12, s[14:15]
	v_add_u32_e32 v12, 0x8000, v12
	global_load_dwordx4 v[32:35], v12, s[14:15]
	v_add_u32_e32 v12, 0x8000, v12
	global_load_dwordx4 v[36:39], v12, s[14:15]
	v_add_u32_e32 v12, 0x8000, v12
	global_load_dwordx4 v[40:43], v12, s[14:15]
	v_add_u32_e32 v12, 0x8000, v12
	global_load_dwordx4 v[44:47], v12, s[14:15]
	s_waitcnt vmcnt(7)
	ds_write_b32 v14, v16 offset:0
	ds_write_b32 v14, v17 offset:4
	ds_write_b32 v14, v18 offset:8
	ds_write_b32 v14, v19 offset:12
	s_waitcnt vmcnt(6)
	ds_write_b32 v14, v20 offset:1056
	ds_write_b32 v14, v21 offset:1060
	ds_write_b32 v14, v22 offset:1064
	ds_write_b32 v14, v23 offset:1068
	s_waitcnt vmcnt(5)
	ds_write_b32 v14, v24 offset:2112
	ds_write_b32 v14, v25 offset:2116
	ds_write_b32 v14, v26 offset:2120
	ds_write_b32 v14, v27 offset:2124
	s_waitcnt vmcnt(4)
	ds_write_b32 v14, v28 offset:3168
	ds_write_b32 v14, v29 offset:3172
	ds_write_b32 v14, v30 offset:3176
	ds_write_b32 v14, v31 offset:3180
	s_waitcnt vmcnt(3)
	ds_write_b32 v14, v32 offset:4224
	ds_write_b32 v14, v33 offset:4228
	ds_write_b32 v14, v34 offset:4232
	ds_write_b32 v14, v35 offset:4236
	s_waitcnt vmcnt(2)
	ds_write_b32 v14, v36 offset:5280
	ds_write_b32 v14, v37 offset:5284
	ds_write_b32 v14, v38 offset:5288
	ds_write_b32 v14, v39 offset:5292
	s_waitcnt vmcnt(1)
	ds_write_b32 v14, v40 offset:6336
	ds_write_b32 v14, v41 offset:6340
	ds_write_b32 v14, v42 offset:6344
	ds_write_b32 v14, v43 offset:6348
	s_waitcnt vmcnt(0)
	ds_write_b32 v14, v44 offset:7392
	ds_write_b32 v14, v45 offset:7396
	ds_write_b32 v14, v46 offset:7400
	ds_write_b32 v14, v47 offset:7404
	s_waitcnt lgkmcnt(0)
	ds_read2_b32 v[80:81], v15 offset0:0 offset1:33
	ds_read2_b32 v[82:83], v15 offset0:66 offset1:99
	ds_read2_b32 v[84:85], v15 offset0:132 offset1:165
	ds_read2_b32 v[86:87], v15 offset0:198 offset1:231
	ds_read2_b32 v[88:89], v15 offset0:8 offset1:41
	ds_read2_b32 v[90:91], v15 offset0:74 offset1:107
	ds_read2_b32 v[92:93], v15 offset0:140 offset1:173
	ds_read2_b32 v[94:95], v15 offset0:206 offset1:239
	s_waitcnt lgkmcnt(4)
	v_cvt_pk_bf16_f32 v112, v80, v81
	v_cvt_pk_bf16_f32 v113, v82, v83
	v_cvt_pk_bf16_f32 v114, v84, v85
	v_cvt_pk_bf16_f32 v115, v86, v87
	global_store_dwordx4 v4, v[112:115], s[16:17]
	s_waitcnt lgkmcnt(0)
	v_cvt_pk_bf16_f32 v116, v88, v89
	v_cvt_pk_bf16_f32 v117, v90, v91
	v_cvt_pk_bf16_f32 v118, v92, v93
	v_cvt_pk_bf16_f32 v119, v94, v95
	global_store_dwordx4 v5, v[116:119], s[16:17]
	ds_read2_b32 v[96:97], v15 offset0:16 offset1:49
	ds_read2_b32 v[98:99], v15 offset0:82 offset1:115
	ds_read2_b32 v[100:101], v15 offset0:148 offset1:181
	ds_read2_b32 v[102:103], v15 offset0:214 offset1:247
	ds_read2_b32 v[104:105], v15 offset0:24 offset1:57
	ds_read2_b32 v[106:107], v15 offset0:90 offset1:123
	ds_read2_b32 v[108:109], v15 offset0:156 offset1:189
	ds_read2_b32 v[110:111], v15 offset0:222 offset1:255
	s_waitcnt lgkmcnt(4)
	v_cvt_pk_bf16_f32 v120, v96, v97
	v_cvt_pk_bf16_f32 v121, v98, v99
	v_cvt_pk_bf16_f32 v122, v100, v101
	v_cvt_pk_bf16_f32 v123, v102, v103
	global_store_dwordx4 v6, v[120:123], s[16:17]
	s_waitcnt lgkmcnt(0)
	v_cvt_pk_bf16_f32 v124, v104, v105
	v_cvt_pk_bf16_f32 v125, v106, v107
	v_cvt_pk_bf16_f32 v126, v108, v109
	v_cvt_pk_bf16_f32 v127, v110, v111
	global_store_dwordx4 v7, v[124:127], s[16:17]
	s_addk_i32 s26, 0x3e0
	s_branch .Lffn2w_w4
